# first workgroup to arrive on each XCD issues one early L2 writeback
# baseline (speedup 1.0000x reference)
.LBB0_819:
	s_or_b64 exec, exec, s[12:13]
	v_cvt_f32_u32_e32 v5, v3
	s_waitcnt vmcnt(0)
	v_readfirstlane_b32 s0, v4
	v_sub_u32_e32 v4, 0, v3
	v_rcp_iflag_f32_e32 v5, v5
	v_add_u32_e32 v6, s0, v2
	v_mul_f32_e32 v5, 0x4f7ffffe, v5
	v_cvt_u32_f32_e32 v5, v5
	v_mul_lo_u32 v2, v4, v5
	v_mul_hi_u32 v2, v5, v2
	v_add_u32_e32 v2, v5, v2
	v_mul_hi_u32 v2, v6, v2
	v_mul_lo_u32 v4, v2, v3
	v_sub_u32_e32 v4, v6, v4
	v_add_u32_e32 v5, 1, v2
	v_cmp_ge_u32_e32 vcc, v4, v3
	s_nop 1
	v_cndmask_b32_e32 v2, v2, v5, vcc
	v_sub_u32_e32 v5, v4, v3
	v_cndmask_b32_e32 v4, v4, v5, vcc
	v_add_u32_e32 v5, 1, v2
	v_cmp_ge_u32_e32 vcc, v4, v3
	v_add_u32_e32 v4, 1, v6
	s_nop 0
	v_cndmask_b32_e32 v2, v2, v5, vcc
	v_mul_lo_u32 v5, v3, v2
	v_add_u32_e32 v3, v5, v3
	v_cmp_ne_u32_e32 vcc, v4, v3
	s_and_saveexec_b64 s[0:1], vcc
	s_xor_b64 s[10:11], exec, s[0:1]
	s_cbranch_execz .LBB0_833
	s_waitcnt lgkmcnt(0)
	v_cmp_eq_u32_e32 vcc, v6, v5
	s_cbranch_vccz .Lseam_no_prewb
	buffer_wbl2 sc1
.Lseam_no_prewb:
	s_add_u32 s14, s78, 0x24703500
	s_addc_u32 s15, s79, 0
	global_load_dword v1, v0, s[14:15] sc1
	s_waitcnt vmcnt(0)
	v_cmp_eq_u32_e32 vcc, v1, v2
	s_and_saveexec_b64 s[12:13], vcc
	s_cbranch_execz .LBB0_832
	s_mov_b32 s0, 1
	s_mov_b64 s[16:17], 0
	s_branch .LBB0_823
